# ffn gate/up GEMM epilogue rewritten by hand: 8 independent silu chains at a time (same op order) and n=0/n=1 pieces paired with v_permlane16_swap into dwordx4 stores
# speedup vs baseline: 1.0638x; 1.0157x over previous
.LBB0_1211:
	s_and_b64 vcc, exec, s[30:31]
	s_cbranch_vccz .LBB0_1213
	v_mov_b64_e32 v[2:3], s[42:43]
	s_movk_i32 s20, 0x1600
	v_and_b32_e32 v198, 1, v235
	v_mul_u32_u24_e32 v198, 24, v198
	v_lshl_or_b32 v196, s1, 7, v146
	v_lshl_add_u32 v196, v196, 1, v198
	v_mov_b32_e32 v197, 0
	v_add_u32_e32 v0, s5, v236
	v_mad_i64_i32 v[192:193], s[0:1], v0, s20, v[2:3]
	v_mul_f32_e32 v184, 0xbfb8aa3b, v128
	v_mul_f32_e32 v185, 0xbfb8aa3b, v129
	v_mul_f32_e32 v186, 0xbfb8aa3b, v130
	v_mul_f32_e32 v187, 0xbfb8aa3b, v131
	v_mul_f32_e32 v188, 0xbfb8aa3b, v124
	v_mul_f32_e32 v189, 0xbfb8aa3b, v125
	v_mul_f32_e32 v190, 0xbfb8aa3b, v126
	v_mul_f32_e32 v191, 0xbfb8aa3b, v127
	v_exp_f32_e32 v184, v184
	v_exp_f32_e32 v185, v185
	v_exp_f32_e32 v186, v186
	v_exp_f32_e32 v187, v187
	v_exp_f32_e32 v188, v188
	v_exp_f32_e32 v189, v189
	v_exp_f32_e32 v190, v190
	v_exp_f32_e32 v191, v191
	v_lshl_add_u64 v[192:193], v[192:193], 0, v[196:197]
	v_add_f32_e32 v184, 1.0, v184
	v_add_f32_e32 v185, 1.0, v185
	v_add_f32_e32 v186, 1.0, v186
	v_add_f32_e32 v187, 1.0, v187
	v_add_f32_e32 v188, 1.0, v188
	v_add_f32_e32 v189, 1.0, v189
	v_add_f32_e32 v190, 1.0, v190
	v_add_f32_e32 v191, 1.0, v191
	v_rcp_f32_e32 v184, v184
	v_rcp_f32_e32 v185, v185
	v_rcp_f32_e32 v186, v186
	v_rcp_f32_e32 v187, v187
	v_rcp_f32_e32 v188, v188
	v_rcp_f32_e32 v189, v189
	v_rcp_f32_e32 v190, v190
	v_rcp_f32_e32 v191, v191
	v_mul_f32_e32 v184, v128, v184
	v_mul_f32_e32 v185, v129, v185
	v_mul_f32_e32 v186, v130, v186
	v_mul_f32_e32 v187, v131, v187
	v_mul_f32_e32 v188, v124, v188
	v_mul_f32_e32 v189, v125, v189
	v_mul_f32_e32 v190, v126, v190
	v_mul_f32_e32 v191, v127, v191
	v_mul_f32_e32 v184, v120, v184
	v_mul_f32_e32 v185, v121, v185
	v_mul_f32_e32 v186, v122, v186
	v_mul_f32_e32 v187, v123, v187
	v_mul_f32_e32 v188, v116, v188
	v_mul_f32_e32 v189, v117, v189
	v_mul_f32_e32 v190, v118, v190
	v_mul_f32_e32 v191, v119, v191
	v_cvt_pk_bf16_f32 v176, v184, v185
	v_cvt_pk_bf16_f32 v177, v186, v187
	v_cvt_pk_bf16_f32 v178, v188, v189
	v_cvt_pk_bf16_f32 v179, v190, v191
	s_nop 1
	v_permlane16_swap_b32_e32 v176, v178
	v_permlane16_swap_b32_e32 v177, v179
	global_store_dwordx4 v[192:193], v[176:179], off
	v_add_u32_e32 v0, s5, v238
	v_mad_i64_i32 v[194:195], s[0:1], v0, s20, v[2:3]
	v_mul_f32_e32 v184, 0xbfb8aa3b, v112
	v_mul_f32_e32 v185, 0xbfb8aa3b, v113
	v_mul_f32_e32 v186, 0xbfb8aa3b, v114
	v_mul_f32_e32 v187, 0xbfb8aa3b, v115
	v_mul_f32_e32 v188, 0xbfb8aa3b, v108
	v_mul_f32_e32 v189, 0xbfb8aa3b, v109
	v_mul_f32_e32 v190, 0xbfb8aa3b, v110
	v_mul_f32_e32 v191, 0xbfb8aa3b, v111
	v_exp_f32_e32 v184, v184
	v_exp_f32_e32 v185, v185
	v_exp_f32_e32 v186, v186
	v_exp_f32_e32 v187, v187
	v_exp_f32_e32 v188, v188
	v_exp_f32_e32 v189, v189
	v_exp_f32_e32 v190, v190
	v_exp_f32_e32 v191, v191
	v_lshl_add_u64 v[194:195], v[194:195], 0, v[196:197]
	v_add_f32_e32 v184, 1.0, v184
	v_add_f32_e32 v185, 1.0, v185
	v_add_f32_e32 v186, 1.0, v186
	v_add_f32_e32 v187, 1.0, v187
	v_add_f32_e32 v188, 1.0, v188
	v_add_f32_e32 v189, 1.0, v189
	v_add_f32_e32 v190, 1.0, v190
	v_add_f32_e32 v191, 1.0, v191
	v_rcp_f32_e32 v184, v184
	v_rcp_f32_e32 v185, v185
	v_rcp_f32_e32 v186, v186
	v_rcp_f32_e32 v187, v187
	v_rcp_f32_e32 v188, v188
	v_rcp_f32_e32 v189, v189
	v_rcp_f32_e32 v190, v190
	v_rcp_f32_e32 v191, v191
	v_mul_f32_e32 v184, v112, v184
	v_mul_f32_e32 v185, v113, v185
	v_mul_f32_e32 v186, v114, v186
	v_mul_f32_e32 v187, v115, v187
	v_mul_f32_e32 v188, v108, v188
	v_mul_f32_e32 v189, v109, v189
	v_mul_f32_e32 v190, v110, v190
	v_mul_f32_e32 v191, v111, v191
	v_mul_f32_e32 v184, v104, v184
	v_mul_f32_e32 v185, v105, v185
	v_mul_f32_e32 v186, v106, v186
	v_mul_f32_e32 v187, v107, v187
	v_mul_f32_e32 v188, v100, v188
	v_mul_f32_e32 v189, v101, v189
	v_mul_f32_e32 v190, v102, v190
	v_mul_f32_e32 v191, v103, v191
	v_cvt_pk_bf16_f32 v180, v184, v185
	v_cvt_pk_bf16_f32 v181, v186, v187
	v_cvt_pk_bf16_f32 v182, v188, v189
	v_cvt_pk_bf16_f32 v183, v190, v191
	s_nop 1
	v_permlane16_swap_b32_e32 v180, v182
	v_permlane16_swap_b32_e32 v181, v183
	global_store_dwordx4 v[194:195], v[180:183], off
	v_add_u32_e32 v0, s5, v239
	v_mad_i64_i32 v[192:193], s[0:1], v0, s20, v[2:3]
	v_mul_f32_e32 v184, 0xbfb8aa3b, v96
	v_mul_f32_e32 v185, 0xbfb8aa3b, v97
	v_mul_f32_e32 v186, 0xbfb8aa3b, v98
	v_mul_f32_e32 v187, 0xbfb8aa3b, v99
	v_mul_f32_e32 v188, 0xbfb8aa3b, v92
	v_mul_f32_e32 v189, 0xbfb8aa3b, v93
	v_mul_f32_e32 v190, 0xbfb8aa3b, v94
	v_mul_f32_e32 v191, 0xbfb8aa3b, v95
	v_exp_f32_e32 v184, v184
	v_exp_f32_e32 v185, v185
	v_exp_f32_e32 v186, v186
	v_exp_f32_e32 v187, v187
	v_exp_f32_e32 v188, v188
	v_exp_f32_e32 v189, v189
	v_exp_f32_e32 v190, v190
	v_exp_f32_e32 v191, v191
	v_lshl_add_u64 v[192:193], v[192:193], 0, v[196:197]
	v_add_f32_e32 v184, 1.0, v184
	v_add_f32_e32 v185, 1.0, v185
	v_add_f32_e32 v186, 1.0, v186
	v_add_f32_e32 v187, 1.0, v187
	v_add_f32_e32 v188, 1.0, v188
	v_add_f32_e32 v189, 1.0, v189
	v_add_f32_e32 v190, 1.0, v190
	v_add_f32_e32 v191, 1.0, v191
	v_rcp_f32_e32 v184, v184
	v_rcp_f32_e32 v185, v185
	v_rcp_f32_e32 v186, v186
	v_rcp_f32_e32 v187, v187
	v_rcp_f32_e32 v188, v188
	v_rcp_f32_e32 v189, v189
	v_rcp_f32_e32 v190, v190
	v_rcp_f32_e32 v191, v191
	v_mul_f32_e32 v184, v96, v184
	v_mul_f32_e32 v185, v97, v185
	v_mul_f32_e32 v186, v98, v186
	v_mul_f32_e32 v187, v99, v187
	v_mul_f32_e32 v188, v92, v188
	v_mul_f32_e32 v189, v93, v189
	v_mul_f32_e32 v190, v94, v190
	v_mul_f32_e32 v191, v95, v191
	v_mul_f32_e32 v184, v88, v184
	v_mul_f32_e32 v185, v89, v185
	v_mul_f32_e32 v186, v90, v186
	v_mul_f32_e32 v187, v91, v187
	v_mul_f32_e32 v188, v84, v188
	v_mul_f32_e32 v189, v85, v189
	v_mul_f32_e32 v190, v86, v190
	v_mul_f32_e32 v191, v87, v191
	v_cvt_pk_bf16_f32 v176, v184, v185
	v_cvt_pk_bf16_f32 v177, v186, v187
	v_cvt_pk_bf16_f32 v178, v188, v189
	v_cvt_pk_bf16_f32 v179, v190, v191
	s_nop 1
	v_permlane16_swap_b32_e32 v176, v178
	v_permlane16_swap_b32_e32 v177, v179
	global_store_dwordx4 v[192:193], v[176:179], off
	v_add_u32_e32 v0, s5, v240
	v_mad_i64_i32 v[194:195], s[0:1], v0, s20, v[2:3]
	v_mul_f32_e32 v184, 0xbfb8aa3b, v80
	v_mul_f32_e32 v185, 0xbfb8aa3b, v81
	v_mul_f32_e32 v186, 0xbfb8aa3b, v82
	v_mul_f32_e32 v187, 0xbfb8aa3b, v83
	v_mul_f32_e32 v188, 0xbfb8aa3b, v76
	v_mul_f32_e32 v189, 0xbfb8aa3b, v77
	v_mul_f32_e32 v190, 0xbfb8aa3b, v78
	v_mul_f32_e32 v191, 0xbfb8aa3b, v79
	v_exp_f32_e32 v184, v184
	v_exp_f32_e32 v185, v185
	v_exp_f32_e32 v186, v186
	v_exp_f32_e32 v187, v187
	v_exp_f32_e32 v188, v188
	v_exp_f32_e32 v189, v189
	v_exp_f32_e32 v190, v190
	v_exp_f32_e32 v191, v191
	v_lshl_add_u64 v[194:195], v[194:195], 0, v[196:197]
	v_add_f32_e32 v184, 1.0, v184
	v_add_f32_e32 v185, 1.0, v185
	v_add_f32_e32 v186, 1.0, v186
	v_add_f32_e32 v187, 1.0, v187
	v_add_f32_e32 v188, 1.0, v188
	v_add_f32_e32 v189, 1.0, v189
	v_add_f32_e32 v190, 1.0, v190
	v_add_f32_e32 v191, 1.0, v191
	v_rcp_f32_e32 v184, v184
	v_rcp_f32_e32 v185, v185
	v_rcp_f32_e32 v186, v186
	v_rcp_f32_e32 v187, v187
	v_rcp_f32_e32 v188, v188
	v_rcp_f32_e32 v189, v189
	v_rcp_f32_e32 v190, v190
	v_rcp_f32_e32 v191, v191
	v_mul_f32_e32 v184, v80, v184
	v_mul_f32_e32 v185, v81, v185
	v_mul_f32_e32 v186, v82, v186
	v_mul_f32_e32 v187, v83, v187
	v_mul_f32_e32 v188, v76, v188
	v_mul_f32_e32 v189, v77, v189
	v_mul_f32_e32 v190, v78, v190
	v_mul_f32_e32 v191, v79, v191
	v_mul_f32_e32 v184, v72, v184
	v_mul_f32_e32 v185, v73, v185
	v_mul_f32_e32 v186, v74, v186
	v_mul_f32_e32 v187, v75, v187
	v_mul_f32_e32 v188, v68, v188
	v_mul_f32_e32 v189, v69, v189
	v_mul_f32_e32 v190, v70, v190
	v_mul_f32_e32 v191, v71, v191
	v_cvt_pk_bf16_f32 v180, v184, v185
	v_cvt_pk_bf16_f32 v181, v186, v187
	v_cvt_pk_bf16_f32 v182, v188, v189
	v_cvt_pk_bf16_f32 v183, v190, v191
	s_nop 1
	v_permlane16_swap_b32_e32 v180, v182
	v_permlane16_swap_b32_e32 v181, v183
	global_store_dwordx4 v[194:195], v[180:183], off
	v_add_u32_e32 v0, s5, v241
	v_mad_i64_i32 v[192:193], s[0:1], v0, s20, v[2:3]
	v_mul_f32_e32 v184, 0xbfb8aa3b, v64
	v_mul_f32_e32 v185, 0xbfb8aa3b, v65
	v_mul_f32_e32 v186, 0xbfb8aa3b, v66
	v_mul_f32_e32 v187, 0xbfb8aa3b, v67
	v_mul_f32_e32 v188, 0xbfb8aa3b, v60
	v_mul_f32_e32 v189, 0xbfb8aa3b, v61
	v_mul_f32_e32 v190, 0xbfb8aa3b, v62
	v_mul_f32_e32 v191, 0xbfb8aa3b, v63
	v_exp_f32_e32 v184, v184
	v_exp_f32_e32 v185, v185
	v_exp_f32_e32 v186, v186
	v_exp_f32_e32 v187, v187
	v_exp_f32_e32 v188, v188
	v_exp_f32_e32 v189, v189
	v_exp_f32_e32 v190, v190
	v_exp_f32_e32 v191, v191
	v_lshl_add_u64 v[192:193], v[192:193], 0, v[196:197]
	v_add_f32_e32 v184, 1.0, v184
	v_add_f32_e32 v185, 1.0, v185
	v_add_f32_e32 v186, 1.0, v186
	v_add_f32_e32 v187, 1.0, v187
	v_add_f32_e32 v188, 1.0, v188
	v_add_f32_e32 v189, 1.0, v189
	v_add_f32_e32 v190, 1.0, v190
	v_add_f32_e32 v191, 1.0, v191
	v_rcp_f32_e32 v184, v184
	v_rcp_f32_e32 v185, v185
	v_rcp_f32_e32 v186, v186
	v_rcp_f32_e32 v187, v187
	v_rcp_f32_e32 v188, v188
	v_rcp_f32_e32 v189, v189
	v_rcp_f32_e32 v190, v190
	v_rcp_f32_e32 v191, v191
	v_mul_f32_e32 v184, v64, v184
	v_mul_f32_e32 v185, v65, v185
	v_mul_f32_e32 v186, v66, v186
	v_mul_f32_e32 v187, v67, v187
	v_mul_f32_e32 v188, v60, v188
	v_mul_f32_e32 v189, v61, v189
	v_mul_f32_e32 v190, v62, v190
	v_mul_f32_e32 v191, v63, v191
	v_mul_f32_e32 v184, v56, v184
	v_mul_f32_e32 v185, v57, v185
	v_mul_f32_e32 v186, v58, v186
	v_mul_f32_e32 v187, v59, v187
	v_mul_f32_e32 v188, v52, v188
	v_mul_f32_e32 v189, v53, v189
	v_mul_f32_e32 v190, v54, v190
	v_mul_f32_e32 v191, v55, v191
	v_cvt_pk_bf16_f32 v176, v184, v185
	v_cvt_pk_bf16_f32 v177, v186, v187
	v_cvt_pk_bf16_f32 v178, v188, v189
	v_cvt_pk_bf16_f32 v179, v190, v191
	s_nop 1
	v_permlane16_swap_b32_e32 v176, v178
	v_permlane16_swap_b32_e32 v177, v179
	global_store_dwordx4 v[192:193], v[176:179], off
	v_add_u32_e32 v0, s5, v242
	v_mad_i64_i32 v[194:195], s[0:1], v0, s20, v[2:3]
	v_mul_f32_e32 v184, 0xbfb8aa3b, v48
	v_mul_f32_e32 v185, 0xbfb8aa3b, v49
	v_mul_f32_e32 v186, 0xbfb8aa3b, v50
	v_mul_f32_e32 v187, 0xbfb8aa3b, v51
	v_mul_f32_e32 v188, 0xbfb8aa3b, v44
	v_mul_f32_e32 v189, 0xbfb8aa3b, v45
	v_mul_f32_e32 v190, 0xbfb8aa3b, v46
	v_mul_f32_e32 v191, 0xbfb8aa3b, v47
	v_exp_f32_e32 v184, v184
	v_exp_f32_e32 v185, v185
	v_exp_f32_e32 v186, v186
	v_exp_f32_e32 v187, v187
	v_exp_f32_e32 v188, v188
	v_exp_f32_e32 v189, v189
	v_exp_f32_e32 v190, v190
	v_exp_f32_e32 v191, v191
	v_lshl_add_u64 v[194:195], v[194:195], 0, v[196:197]
	v_add_f32_e32 v184, 1.0, v184
	v_add_f32_e32 v185, 1.0, v185
	v_add_f32_e32 v186, 1.0, v186
	v_add_f32_e32 v187, 1.0, v187
	v_add_f32_e32 v188, 1.0, v188
	v_add_f32_e32 v189, 1.0, v189
	v_add_f32_e32 v190, 1.0, v190
	v_add_f32_e32 v191, 1.0, v191
	v_rcp_f32_e32 v184, v184
	v_rcp_f32_e32 v185, v185
	v_rcp_f32_e32 v186, v186
	v_rcp_f32_e32 v187, v187
	v_rcp_f32_e32 v188, v188
	v_rcp_f32_e32 v189, v189
	v_rcp_f32_e32 v190, v190
	v_rcp_f32_e32 v191, v191
	v_mul_f32_e32 v184, v48, v184
	v_mul_f32_e32 v185, v49, v185
	v_mul_f32_e32 v186, v50, v186
	v_mul_f32_e32 v187, v51, v187
	v_mul_f32_e32 v188, v44, v188
	v_mul_f32_e32 v189, v45, v189
	v_mul_f32_e32 v190, v46, v190
	v_mul_f32_e32 v191, v47, v191
	v_mul_f32_e32 v184, v40, v184
	v_mul_f32_e32 v185, v41, v185
	v_mul_f32_e32 v186, v42, v186
	v_mul_f32_e32 v187, v43, v187
	v_mul_f32_e32 v188, v36, v188
	v_mul_f32_e32 v189, v37, v189
	v_mul_f32_e32 v190, v38, v190
	v_mul_f32_e32 v191, v39, v191
	v_cvt_pk_bf16_f32 v180, v184, v185
	v_cvt_pk_bf16_f32 v181, v186, v187
	v_cvt_pk_bf16_f32 v182, v188, v189
	v_cvt_pk_bf16_f32 v183, v190, v191
	s_nop 1
	v_permlane16_swap_b32_e32 v180, v182
	v_permlane16_swap_b32_e32 v181, v183
	global_store_dwordx4 v[194:195], v[180:183], off
	v_add_u32_e32 v0, s5, v243
	v_mad_i64_i32 v[192:193], s[0:1], v0, s20, v[2:3]
	v_mul_f32_e32 v184, 0xbfb8aa3b, v32
	v_mul_f32_e32 v185, 0xbfb8aa3b, v33
	v_mul_f32_e32 v186, 0xbfb8aa3b, v34
	v_mul_f32_e32 v187, 0xbfb8aa3b, v35
	v_mul_f32_e32 v188, 0xbfb8aa3b, v28
	v_mul_f32_e32 v189, 0xbfb8aa3b, v29
	v_mul_f32_e32 v190, 0xbfb8aa3b, v30
	v_mul_f32_e32 v191, 0xbfb8aa3b, v31
	v_exp_f32_e32 v184, v184
	v_exp_f32_e32 v185, v185
	v_exp_f32_e32 v186, v186
	v_exp_f32_e32 v187, v187
	v_exp_f32_e32 v188, v188
	v_exp_f32_e32 v189, v189
	v_exp_f32_e32 v190, v190
	v_exp_f32_e32 v191, v191
	v_lshl_add_u64 v[192:193], v[192:193], 0, v[196:197]
	v_add_f32_e32 v184, 1.0, v184
	v_add_f32_e32 v185, 1.0, v185
	v_add_f32_e32 v186, 1.0, v186
	v_add_f32_e32 v187, 1.0, v187
	v_add_f32_e32 v188, 1.0, v188
	v_add_f32_e32 v189, 1.0, v189
	v_add_f32_e32 v190, 1.0, v190
	v_add_f32_e32 v191, 1.0, v191
	v_rcp_f32_e32 v184, v184
	v_rcp_f32_e32 v185, v185
	v_rcp_f32_e32 v186, v186
	v_rcp_f32_e32 v187, v187
	v_rcp_f32_e32 v188, v188
	v_rcp_f32_e32 v189, v189
	v_rcp_f32_e32 v190, v190
	v_rcp_f32_e32 v191, v191
	v_mul_f32_e32 v184, v32, v184
	v_mul_f32_e32 v185, v33, v185
	v_mul_f32_e32 v186, v34, v186
	v_mul_f32_e32 v187, v35, v187
	v_mul_f32_e32 v188, v28, v188
	v_mul_f32_e32 v189, v29, v189
	v_mul_f32_e32 v190, v30, v190
	v_mul_f32_e32 v191, v31, v191
	v_mul_f32_e32 v184, v24, v184
	v_mul_f32_e32 v185, v25, v185
	v_mul_f32_e32 v186, v26, v186
	v_mul_f32_e32 v187, v27, v187
	v_mul_f32_e32 v188, v20, v188
	v_mul_f32_e32 v189, v21, v189
	v_mul_f32_e32 v190, v22, v190
	v_mul_f32_e32 v191, v23, v191
	v_cvt_pk_bf16_f32 v176, v184, v185
	v_cvt_pk_bf16_f32 v177, v186, v187
	v_cvt_pk_bf16_f32 v178, v188, v189
	v_cvt_pk_bf16_f32 v179, v190, v191
	s_nop 1
	v_permlane16_swap_b32_e32 v176, v178
	v_permlane16_swap_b32_e32 v177, v179
	global_store_dwordx4 v[192:193], v[176:179], off
	v_add_u32_e32 v0, s5, v244
	v_mad_i64_i32 v[194:195], s[0:1], v0, s20, v[2:3]
	v_mul_f32_e32 v184, 0xbfb8aa3b, v16
	v_mul_f32_e32 v185, 0xbfb8aa3b, v17
	v_mul_f32_e32 v186, 0xbfb8aa3b, v18
	v_mul_f32_e32 v187, 0xbfb8aa3b, v19
	v_mul_f32_e32 v188, 0xbfb8aa3b, v12
	v_mul_f32_e32 v189, 0xbfb8aa3b, v13
	v_mul_f32_e32 v190, 0xbfb8aa3b, v14
	v_mul_f32_e32 v191, 0xbfb8aa3b, v15
	v_exp_f32_e32 v184, v184
	v_exp_f32_e32 v185, v185
	v_exp_f32_e32 v186, v186
	v_exp_f32_e32 v187, v187
	v_exp_f32_e32 v188, v188
	v_exp_f32_e32 v189, v189
	v_exp_f32_e32 v190, v190
	v_exp_f32_e32 v191, v191
	v_lshl_add_u64 v[194:195], v[194:195], 0, v[196:197]
	v_add_f32_e32 v184, 1.0, v184
	v_add_f32_e32 v185, 1.0, v185
	v_add_f32_e32 v186, 1.0, v186
	v_add_f32_e32 v187, 1.0, v187
	v_add_f32_e32 v188, 1.0, v188
	v_add_f32_e32 v189, 1.0, v189
	v_add_f32_e32 v190, 1.0, v190
	v_add_f32_e32 v191, 1.0, v191
	v_rcp_f32_e32 v184, v184
	v_rcp_f32_e32 v185, v185
	v_rcp_f32_e32 v186, v186
	v_rcp_f32_e32 v187, v187
	v_rcp_f32_e32 v188, v188
	v_rcp_f32_e32 v189, v189
	v_rcp_f32_e32 v190, v190
	v_rcp_f32_e32 v191, v191
	v_mul_f32_e32 v184, v16, v184
	v_mul_f32_e32 v185, v17, v185
	v_mul_f32_e32 v186, v18, v186
	v_mul_f32_e32 v187, v19, v187
	v_mul_f32_e32 v188, v12, v188
	v_mul_f32_e32 v189, v13, v189
	v_mul_f32_e32 v190, v14, v190
	v_mul_f32_e32 v191, v15, v191
	v_mul_f32_e32 v184, v8, v184
	v_mul_f32_e32 v185, v9, v185
	v_mul_f32_e32 v186, v10, v186
	v_mul_f32_e32 v187, v11, v187
	v_mul_f32_e32 v188, v4, v188
	v_mul_f32_e32 v189, v5, v189
	v_mul_f32_e32 v190, v6, v190
	v_mul_f32_e32 v191, v7, v191
	v_cvt_pk_bf16_f32 v180, v184, v185
	v_cvt_pk_bf16_f32 v181, v186, v187
	v_cvt_pk_bf16_f32 v182, v188, v189
	v_cvt_pk_bf16_f32 v183, v190, v191
	s_nop 1
	v_permlane16_swap_b32_e32 v180, v182
	v_permlane16_swap_b32_e32 v181, v183
	global_store_dwordx4 v[194:195], v[180:183], off
